# Up epilogue: all 8 second-half conv-weight loads issued together, single wait before the first token block
# speedup vs baseline: 1.0095x; 1.0021x over previous
.LBB0_849:
	s_or_b64 exec, exec, s[18:19]
	v_or_b32_e32 v64, 4, v184
	v_ashrrev_i32_e32 v65, 31, v64
	v_lshlrev_b64 v[76:77], 2, v[64:65]
	v_lshl_add_u64 v[64:65], s[28:29], 0, v[76:77]
	v_lshl_add_u64 v[66:67], s[30:31], 0, v[76:77]
	v_lshl_add_u64 v[72:73], s[34:35], 0, v[76:77]
	global_load_dwordx4 v[88:91], v[186:187], off offset:16
	global_load_dwordx4 v[92:95], v[64:65], off
	global_load_dwordx4 v[68:71], v[66:67], off
	s_nop 0
	global_load_dwordx4 v[64:67], v[188:189], off offset:16
	v_lshl_add_u64 v[74:75], s[36:37], 0, v[76:77]
	global_load_dwordx4 v[80:83], v[72:73], off
	global_load_dwordx4 v[84:87], v[74:75], off
	v_lshl_add_u64 v[72:73], s[40:41], 0, v[76:77]
	v_lshl_add_u64 v[76:77], s[42:43], 0, v[76:77]
	global_load_dwordx4 v[72:75], v[72:73], off
	global_load_dwordx4 v[76:79], v[76:77], off
	v_mov_b32_dpp v110, v8 row_shr:1 row_mask:0xf bank_mask:0xf bound_ctrl:1
	v_mov_b32_dpp v102, v60 row_shl:1 row_mask:0xf bank_mask:0xf bound_ctrl:1
	v_mov_b32_dpp v108, v0 row_shr:1 row_mask:0xf bank_mask:0xf bound_ctrl:1
	v_mov_b32_dpp v100, v56 row_shl:1 row_mask:0xf bank_mask:0xf bound_ctrl:1
	v_mov_b32_dpp v111, v9 row_shr:1 row_mask:0xf bank_mask:0xf bound_ctrl:1
	v_mov_b32_dpp v103, v61 row_shl:1 row_mask:0xf bank_mask:0xf bound_ctrl:1
	v_mov_b32_dpp v109, v1 row_shr:1 row_mask:0xf bank_mask:0xf bound_ctrl:1
	v_mov_b32_dpp v101, v57 row_shl:1 row_mask:0xf bank_mask:0xf bound_ctrl:1
	v_mov_b32_dpp v106, v10 row_shr:1 row_mask:0xf bank_mask:0xf bound_ctrl:1
	v_mov_b32_dpp v98, v62 row_shl:1 row_mask:0xf bank_mask:0xf bound_ctrl:1
	v_mov_b32_dpp v104, v2 row_shr:1 row_mask:0xf bank_mask:0xf bound_ctrl:1
	v_mov_b32_dpp v96, v58 row_shl:1 row_mask:0xf bank_mask:0xf bound_ctrl:1
	v_mov_b32_dpp v107, v11 row_shr:1 row_mask:0xf bank_mask:0xf bound_ctrl:1
	v_mov_b32_dpp v99, v63 row_shl:1 row_mask:0xf bank_mask:0xf bound_ctrl:1
	v_mov_b32_dpp v105, v3 row_shr:1 row_mask:0xf bank_mask:0xf bound_ctrl:1
	v_mov_b32_dpp v97, v59 row_shl:1 row_mask:0xf bank_mask:0xf bound_ctrl:1
	s_waitcnt vmcnt(0)
	s_and_saveexec_b64 s[18:19], s[50:51]
	s_cbranch_execnz .LBB0_858
	s_or_b64 exec, exec, s[18:19]
	s_and_saveexec_b64 s[18:19], s[52:53]
	s_cbranch_execnz .LBB0_859
